# layer-1/2 compression weight transposes (544 sub-tiles) moved from blocks 0-67 to blocks 128-195, which do not run the rope-table/bias section
# speedup vs baseline: 1.0025x; 1.0025x over previous
.LBB0_345:
	s_load_dwordx8 s[68:75], s[0:1], 0x38
	s_load_dwordx8 s[92:99], s[0:1], 0x60
	s_load_dwordx2 s[20:21], s[0:1], 0x10
	v_readfirstlane_b32 s4, v238
	v_and_b32_e32 v1, 63, v238
	v_lshrrev_b32_e32 v2, 3, v1
	v_and_b32_e32 v3, 7, v1
	v_lshlrev_b32_e32 v58, 2, v3
	s_lshr_b32 s4, s4, 6
	s_lshl_b32 s41, s2, 3
	s_add_i32 s41, s41, s4
	s_mul_i32 s5, s4, 0x2100
	s_addk_i32 s5, 0x1000
	v_mul_u32_u24_e32 v56, 0x84, v2
	v_lshl_add_u32 v56, v3, 4, v56
	v_add_u32_e32 v56, s5, v56
	v_mul_u32_u24_e32 v57, 0x420, v3
	v_lshl_add_u32 v57, v2, 2, v57
	v_add_u32_e32 v57, s5, v57
	v_lshlrev_b32_e32 v13, 2, v2
	s_waitcnt lgkmcnt(0)
	s_sub_u32 s16, s41, 0x400
	s_cmpk_lt_u32 s16, 0x220
	s_cbranch_scc0 .Ltcx_no3a
	s_cmpk_lt_u32 s16, 0x100
	s_cbranch_scc0 .Ltcx_3n4
	s_mov_b64 s[62:63], s[68:69]
	s_mov_b32 s58, 0x1800000
	s_mov_b32 s59, s16
	s_branch .Ltcx_3sel
.Ltcx_3n4:
	s_cmpk_lt_u32 s16, 0x200
	s_cbranch_scc0 .Ltcx_3n5
	s_mov_b64 s[62:63], s[72:73]
	s_mov_b32 s58, 0x1900000
	s_sub_i32 s59, s16, 0x100
	s_branch .Ltcx_3sel
.Ltcx_3n5:
	s_cmpk_lt_u32 s16, 0x210
	s_cbranch_scc0 .Ltcx_3m7
	s_mov_b64 s[62:63], s[70:71]
	s_mov_b32 s58, 0x1a00000
	s_sub_i32 s59, s16, 0x200
	s_branch .Ltcx_3s67
.Ltcx_3m7:
	s_mov_b64 s[62:63], s[74:75]
	s_mov_b32 s58, 0x1a10000
	s_sub_i32 s59, s16, 0x210

.Ltcx_nz0:
	ds_write_b32 v56, v100
	ds_write_b32 v56, v101 offset:4
	ds_write_b32 v56, v102 offset:8
	ds_write_b32 v56, v103 offset:12
	ds_write_b32 v56, v104 offset:1056
	ds_write_b32 v56, v105 offset:1060
	ds_write_b32 v56, v106 offset:1064
	ds_write_b32 v56, v107 offset:1068
	ds_write_b32 v56, v108 offset:2112
	ds_write_b32 v56, v109 offset:2116
	ds_write_b32 v56, v110 offset:2120
	ds_write_b32 v56, v111 offset:2124
	ds_write_b32 v56, v112 offset:3168
	ds_write_b32 v56, v113 offset:3172
	ds_write_b32 v56, v114 offset:3176
	ds_write_b32 v56, v115 offset:3180
	ds_write_b32 v56, v116 offset:4224
	ds_write_b32 v56, v117 offset:4228
	ds_write_b32 v56, v118 offset:4232
	ds_write_b32 v56, v119 offset:4236
	ds_write_b32 v56, v120 offset:5280
	ds_write_b32 v56, v121 offset:5284
	ds_write_b32 v56, v122 offset:5288
	ds_write_b32 v56, v123 offset:5292
	ds_write_b32 v56, v124 offset:6336
	ds_write_b32 v56, v125 offset:6340
	ds_write_b32 v56, v126 offset:6344
	ds_write_b32 v56, v127 offset:6348
	ds_write_b32 v56, v128 offset:7392
	ds_write_b32 v56, v129 offset:7396
	ds_write_b32 v56, v130 offset:7400
	ds_write_b32 v56, v131 offset:7404
	s_waitcnt lgkmcnt(0)
	ds_read2_b32 v[8:9], v57 offset0:0 offset1:33
	ds_read2_b32 v[10:11], v57 offset0:66 offset1:99
	ds_read2_b32 v[12:13], v57 offset0:132 offset1:165
	ds_read2_b32 v[14:15], v57 offset0:198 offset1:231
	ds_read2_b32 v[16:17], v57 offset0:8 offset1:41
	ds_read2_b32 v[18:19], v57 offset0:74 offset1:107
	ds_read2_b32 v[20:21], v57 offset0:140 offset1:173
	ds_read2_b32 v[22:23], v57 offset0:206 offset1:239
	ds_read2_b32 v[24:25], v57 offset0:16 offset1:49
	ds_read2_b32 v[26:27], v57 offset0:82 offset1:115
	ds_read2_b32 v[28:29], v57 offset0:148 offset1:181
	ds_read2_b32 v[30:31], v57 offset0:214 offset1:247
	ds_read2_b32 v[32:33], v57 offset0:24 offset1:57
	ds_read2_b32 v[34:35], v57 offset0:90 offset1:123
	ds_read2_b32 v[36:37], v57 offset0:156 offset1:189
	ds_read2_b32 v[38:39], v57 offset0:222 offset1:255
	s_waitcnt lgkmcnt(12)
	v_cvt_pk_bf16_f32 v40, v8, v9
	v_cvt_pk_bf16_f32 v41, v10, v11
	v_cvt_pk_bf16_f32 v42, v12, v13
	v_cvt_pk_bf16_f32 v43, v14, v15
	global_store_dwordx4 v59, v[40:43], s[22:23]
	s_add_u32 s22, s22, s24
	s_addc_u32 s23, s23, 0
	s_waitcnt lgkmcnt(8)
	v_cvt_pk_bf16_f32 v44, v16, v17
	v_cvt_pk_bf16_f32 v45, v18, v19
	v_cvt_pk_bf16_f32 v46, v20, v21
	v_cvt_pk_bf16_f32 v47, v22, v23
	global_store_dwordx4 v59, v[44:47], s[22:23]
	s_add_u32 s22, s22, s24
	s_addc_u32 s23, s23, 0
	s_waitcnt lgkmcnt(4)
	v_cvt_pk_bf16_f32 v48, v24, v25
	v_cvt_pk_bf16_f32 v49, v26, v27
	v_cvt_pk_bf16_f32 v50, v28, v29
	v_cvt_pk_bf16_f32 v51, v30, v31
	global_store_dwordx4 v59, v[48:51], s[22:23]
	s_add_u32 s22, s22, s24
	s_addc_u32 s23, s23, 0
	s_waitcnt lgkmcnt(0)
	v_cvt_pk_bf16_f32 v52, v32, v33
	v_cvt_pk_bf16_f32 v53, v34, v35
	v_cvt_pk_bf16_f32 v54, v36, v37
	v_cvt_pk_bf16_f32 v55, v38, v39
	global_store_dwordx4 v59, v[52:55], s[22:23]
	v_mul_f32_e32 v132, v132, v228
	v_mul_f32_e32 v133, v133, v228
	v_mul_f32_e32 v134, v134, v228
	v_mul_f32_e32 v135, v135, v228
	v_mul_f32_e32 v136, v136, v229
	v_mul_f32_e32 v137, v137, v229
	v_mul_f32_e32 v138, v138, v229
	v_mul_f32_e32 v139, v139, v229
	v_mul_f32_e32 v140, v140, v230
	v_mul_f32_e32 v141, v141, v230
	v_mul_f32_e32 v142, v142, v230
	v_mul_f32_e32 v143, v143, v230
	v_mul_f32_e32 v144, v144, v231
	v_mul_f32_e32 v145, v145, v231
	v_mul_f32_e32 v146, v146, v231
	v_mul_f32_e32 v147, v147, v231
	v_mul_f32_e32 v148, v148, v232
	v_mul_f32_e32 v149, v149, v232
	v_mul_f32_e32 v150, v150, v232
	v_mul_f32_e32 v151, v151, v232
	v_mul_f32_e32 v152, v152, v233
	v_mul_f32_e32 v153, v153, v233
	v_mul_f32_e32 v154, v154, v233
	v_mul_f32_e32 v155, v155, v233
	v_mul_f32_e32 v156, v156, v234
	v_mul_f32_e32 v157, v157, v234
	v_mul_f32_e32 v158, v158, v234
	v_mul_f32_e32 v159, v159, v234
	v_mul_f32_e32 v160, v160, v235
	v_mul_f32_e32 v161, v161, v235
	v_mul_f32_e32 v162, v162, v235
	v_mul_f32_e32 v163, v163, v235
	ds_write_b32 v56, v132
	ds_write_b32 v56, v133 offset:4
	ds_write_b32 v56, v134 offset:8
	ds_write_b32 v56, v135 offset:12
	ds_write_b32 v56, v136 offset:1056
	ds_write_b32 v56, v137 offset:1060
	ds_write_b32 v56, v138 offset:1064
	ds_write_b32 v56, v139 offset:1068
	ds_write_b32 v56, v140 offset:2112
	ds_write_b32 v56, v141 offset:2116
	ds_write_b32 v56, v142 offset:2120
	ds_write_b32 v56, v143 offset:2124
	ds_write_b32 v56, v144 offset:3168
	ds_write_b32 v56, v145 offset:3172
	ds_write_b32 v56, v146 offset:3176
	ds_write_b32 v56, v147 offset:3180
	ds_write_b32 v56, v148 offset:4224
	ds_write_b32 v56, v149 offset:4228
	ds_write_b32 v56, v150 offset:4232
	ds_write_b32 v56, v151 offset:4236
	ds_write_b32 v56, v152 offset:5280
	ds_write_b32 v56, v153 offset:5284
	ds_write_b32 v56, v154 offset:5288
	ds_write_b32 v56, v155 offset:5292
	ds_write_b32 v56, v156 offset:6336
	ds_write_b32 v56, v157 offset:6340
	ds_write_b32 v56, v158 offset:6344
	ds_write_b32 v56, v159 offset:6348
	ds_write_b32 v56, v160 offset:7392
	ds_write_b32 v56, v161 offset:7396
	ds_write_b32 v56, v162 offset:7400
	ds_write_b32 v56, v163 offset:7404
	s_waitcnt lgkmcnt(0)
	ds_read2_b32 v[8:9], v57 offset0:0 offset1:33
	ds_read2_b32 v[10:11], v57 offset0:66 offset1:99
	ds_read2_b32 v[12:13], v57 offset0:132 offset1:165
	ds_read2_b32 v[14:15], v57 offset0:198 offset1:231
	ds_read2_b32 v[16:17], v57 offset0:8 offset1:41
	ds_read2_b32 v[18:19], v57 offset0:74 offset1:107
	ds_read2_b32 v[20:21], v57 offset0:140 offset1:173
	ds_read2_b32 v[22:23], v57 offset0:206 offset1:239
	ds_read2_b32 v[24:25], v57 offset0:16 offset1:49
	ds_read2_b32 v[26:27], v57 offset0:82 offset1:115
	ds_read2_b32 v[28:29], v57 offset0:148 offset1:181
	ds_read2_b32 v[30:31], v57 offset0:214 offset1:247
	ds_read2_b32 v[32:33], v57 offset0:24 offset1:57
	ds_read2_b32 v[34:35], v57 offset0:90 offset1:123
	ds_read2_b32 v[36:37], v57 offset0:156 offset1:189
	ds_read2_b32 v[38:39], v57 offset0:222 offset1:255
	s_waitcnt lgkmcnt(12)
	v_cvt_pk_bf16_f32 v40, v8, v9
	v_cvt_pk_bf16_f32 v41, v10, v11
	v_cvt_pk_bf16_f32 v42, v12, v13
	v_cvt_pk_bf16_f32 v43, v14, v15
	global_store_dwordx4 v60, v[40:43], s[26:27]
	s_add_u32 s26, s26, s25
	s_addc_u32 s27, s27, 0
	s_waitcnt lgkmcnt(8)
	v_cvt_pk_bf16_f32 v44, v16, v17
	v_cvt_pk_bf16_f32 v45, v18, v19
	v_cvt_pk_bf16_f32 v46, v20, v21
	v_cvt_pk_bf16_f32 v47, v22, v23
	global_store_dwordx4 v60, v[44:47], s[26:27]
	s_add_u32 s26, s26, s25
	s_addc_u32 s27, s27, 0
	s_waitcnt lgkmcnt(4)
	v_cvt_pk_bf16_f32 v48, v24, v25
	v_cvt_pk_bf16_f32 v49, v26, v27
	v_cvt_pk_bf16_f32 v50, v28, v29
	v_cvt_pk_bf16_f32 v51, v30, v31
	global_store_dwordx4 v60, v[48:51], s[26:27]
	s_add_u32 s26, s26, s25
	s_addc_u32 s27, s27, 0
	s_waitcnt lgkmcnt(0)
	v_cvt_pk_bf16_f32 v52, v32, v33
	v_cvt_pk_bf16_f32 v53, v34, v35
	v_cvt_pk_bf16_f32 v54, v36, v37
	v_cvt_pk_bf16_f32 v55, v38, v39
	global_store_dwordx4 v60, v[52:55], s[26:27]
	ds_write_b32 v56, v164
	ds_write_b32 v56, v165 offset:4
	ds_write_b32 v56, v166 offset:8
	ds_write_b32 v56, v167 offset:12
	ds_write_b32 v56, v168 offset:1056
	ds_write_b32 v56, v169 offset:1060
	ds_write_b32 v56, v170 offset:1064
	ds_write_b32 v56, v171 offset:1068
	ds_write_b32 v56, v172 offset:2112
	ds_write_b32 v56, v173 offset:2116
	ds_write_b32 v56, v174 offset:2120
	ds_write_b32 v56, v175 offset:2124
	ds_write_b32 v56, v176 offset:3168
	ds_write_b32 v56, v177 offset:3172
	ds_write_b32 v56, v178 offset:3176
	ds_write_b32 v56, v179 offset:3180
	ds_write_b32 v56, v180 offset:4224
	ds_write_b32 v56, v181 offset:4228
	ds_write_b32 v56, v182 offset:4232
	ds_write_b32 v56, v183 offset:4236
	ds_write_b32 v56, v184 offset:5280
	ds_write_b32 v56, v185 offset:5284
	ds_write_b32 v56, v186 offset:5288
	ds_write_b32 v56, v187 offset:5292
	ds_write_b32 v56, v188 offset:6336
	ds_write_b32 v56, v189 offset:6340
	ds_write_b32 v56, v190 offset:6344
	ds_write_b32 v56, v191 offset:6348
	ds_write_b32 v56, v192 offset:7392
	ds_write_b32 v56, v193 offset:7396
	ds_write_b32 v56, v194 offset:7400
	ds_write_b32 v56, v195 offset:7404
	s_waitcnt lgkmcnt(0)
	ds_read2_b32 v[8:9], v57 offset0:0 offset1:33
	ds_read2_b32 v[10:11], v57 offset0:66 offset1:99
	ds_read2_b32 v[12:13], v57 offset0:132 offset1:165
	ds_read2_b32 v[14:15], v57 offset0:198 offset1:231
	ds_read2_b32 v[16:17], v57 offset0:8 offset1:41
	ds_read2_b32 v[18:19], v57 offset0:74 offset1:107
	ds_read2_b32 v[20:21], v57 offset0:140 offset1:173
	ds_read2_b32 v[22:23], v57 offset0:206 offset1:239
	ds_read2_b32 v[24:25], v57 offset0:16 offset1:49
	ds_read2_b32 v[26:27], v57 offset0:82 offset1:115
	ds_read2_b32 v[28:29], v57 offset0:148 offset1:181
	ds_read2_b32 v[30:31], v57 offset0:214 offset1:247
	ds_read2_b32 v[32:33], v57 offset0:24 offset1:57
	ds_read2_b32 v[34:35], v57 offset0:90 offset1:123
	ds_read2_b32 v[36:37], v57 offset0:156 offset1:189
	ds_read2_b32 v[38:39], v57 offset0:222 offset1:255
	s_waitcnt lgkmcnt(12)
	v_cvt_pk_bf16_f32 v40, v8, v9
	v_cvt_pk_bf16_f32 v41, v10, v11
	v_cvt_pk_bf16_f32 v42, v12, v13
	v_cvt_pk_bf16_f32 v43, v14, v15
	global_store_dwordx4 v61, v[40:43], s[30:31]
	s_add_u32 s30, s30, s32
	s_addc_u32 s31, s31, 0
	s_waitcnt lgkmcnt(8)
	v_cvt_pk_bf16_f32 v44, v16, v17
	v_cvt_pk_bf16_f32 v45, v18, v19
	v_cvt_pk_bf16_f32 v46, v20, v21
	v_cvt_pk_bf16_f32 v47, v22, v23
	global_store_dwordx4 v61, v[44:47], s[30:31]
	s_add_u32 s30, s30, s32
	s_addc_u32 s31, s31, 0
	s_waitcnt lgkmcnt(4)
	v_cvt_pk_bf16_f32 v48, v24, v25
	v_cvt_pk_bf16_f32 v49, v26, v27
	v_cvt_pk_bf16_f32 v50, v28, v29
	v_cvt_pk_bf16_f32 v51, v30, v31
	global_store_dwordx4 v61, v[48:51], s[30:31]
	s_add_u32 s30, s30, s32
	s_addc_u32 s31, s31, 0
	s_waitcnt lgkmcnt(0)
	v_cvt_pk_bf16_f32 v52, v32, v33
	v_cvt_pk_bf16_f32 v53, v34, v35
	v_cvt_pk_bf16_f32 v54, v36, v37
	v_cvt_pk_bf16_f32 v55, v38, v39
	global_store_dwordx4 v61, v[52:55], s[30:31]
	s_sub_u32 s4, s41, 0x400
	s_cmpk_lt_u32 s4, 0x220
	s_cbranch_scc0 .Ltcx_done
	s_cmp_eq_u32 s39, 32
	s_cbranch_scc1 .Ltcx_nz3
	v_cmp_gt_u32_e32 vcc, s39, v58
	s_nop 1
	v_cndmask_b32_e32 v196, 0, v196, vcc
	v_cndmask_b32_e32 v197, 0, v197, vcc
	v_cndmask_b32_e32 v198, 0, v198, vcc
	v_cndmask_b32_e32 v199, 0, v199, vcc
	v_cndmask_b32_e32 v200, 0, v200, vcc
	v_cndmask_b32_e32 v201, 0, v201, vcc
	v_cndmask_b32_e32 v202, 0, v202, vcc
	v_cndmask_b32_e32 v203, 0, v203, vcc
	v_cndmask_b32_e32 v204, 0, v204, vcc
	v_cndmask_b32_e32 v205, 0, v205, vcc
	v_cndmask_b32_e32 v206, 0, v206, vcc
	v_cndmask_b32_e32 v207, 0, v207, vcc
	v_cndmask_b32_e32 v208, 0, v208, vcc
	v_cndmask_b32_e32 v209, 0, v209, vcc
	v_cndmask_b32_e32 v210, 0, v210, vcc
	v_cndmask_b32_e32 v211, 0, v211, vcc
	v_cndmask_b32_e32 v212, 0, v212, vcc
	v_cndmask_b32_e32 v213, 0, v213, vcc
	v_cndmask_b32_e32 v214, 0, v214, vcc
	v_cndmask_b32_e32 v215, 0, v215, vcc
	v_cndmask_b32_e32 v216, 0, v216, vcc
	v_cndmask_b32_e32 v217, 0, v217, vcc
	v_cndmask_b32_e32 v218, 0, v218, vcc
	v_cndmask_b32_e32 v219, 0, v219, vcc
	v_cndmask_b32_e32 v220, 0, v220, vcc
	v_cndmask_b32_e32 v221, 0, v221, vcc
	v_cndmask_b32_e32 v222, 0, v222, vcc
	v_cndmask_b32_e32 v223, 0, v223, vcc
	v_cndmask_b32_e32 v224, 0, v224, vcc
	v_cndmask_b32_e32 v225, 0, v225, vcc
	v_cndmask_b32_e32 v226, 0, v226, vcc
	v_cndmask_b32_e32 v227, 0, v227, vcc
